# attention loops: the 16 bias-table LDS reads of a bias tile pipelined 8 deep with counted lgkmcnt (were 8 serialized read-pair round trips), in both the band and the differential loop
# baseline (speedup 1.0000x reference)
; #define ATT_VLD(i_) lds_rd(stv, ((((i_) % (DV / 16)) * 2) + ((i_) / (DV / 16))) * 1024)
; template <int DV, int NMAP> ...
;     ...
;             bf16x8 v0 = ATT_VLD(0), v1 = ATT_VLD(1), v2 = ATT_VLD(2);
;             __builtin_amdgcn_sched_barrier(0);
;             if (t >= cw - 2) {
;                 const int tb = 64 * (t - cw + 2) + 8 * fq + 63 - qoff - fr;
; #pragma unroll
;                 for (int kb = 0; kb < 4; ++kb)
; #pragma unroll
;                     for (int qb = 0; qb < 2; ++qb)
; #pragma unroll
;                         for (int i = 0; i < 4; ++i) s[kb][qb][i] += tab[tb + 32 * (kb >> 1) + 4 * (kb & 1) + i - 16 * qb];
;             }
.LBB0_325:
	v_add_u32_e32 v184, s44, v238
	v_add_u32_e32 v204, 0x8000, v184
	ds_read_b128 v[200:203], v204 offset:0
	ds_read_b128 v[192:195], v204 offset:0x800
	ds_read_b128 v[184:187], v204 offset:0x1000
	s_cmp_lt_i32 s84, s68
	s_cbranch_scc1 .LBB0_318
	ds_read2_b32 v[206:207], v239 offset0:16 offset1:17
	ds_read2_b32 v[208:209], v239 offset0:18 offset1:19
	ds_read2_b32 v[240:241], v239 offset1:1
	ds_read2_b32 v[242:243], v239 offset0:2 offset1:3
	ds_read2_b32 v[244:245], v239 offset0:20 offset1:21
	ds_read2_b32 v[246:247], v239 offset0:22 offset1:23
	ds_read2_b32 v[248:249], v239 offset0:4 offset1:5
	ds_read2_b32 v[250:251], v239 offset0:6 offset1:7
	s_waitcnt lgkmcnt(6)
	v_pk_add_f32 v[196:197], v[196:197], v[206:207]
	v_pk_add_f32 v[198:199], v[198:199], v[208:209]
	ds_read2_b32 v[206:207], v239 offset0:48 offset1:49
	ds_read2_b32 v[208:209], v239 offset0:50 offset1:51
	s_waitcnt lgkmcnt(6)
	v_pk_add_f32 v[180:181], v[180:181], v[240:241]
	v_pk_add_f32 v[182:183], v[182:183], v[242:243]
	ds_read2_b32 v[240:241], v239 offset0:32 offset1:33
	ds_read2_b32 v[242:243], v239 offset0:34 offset1:35
	s_waitcnt lgkmcnt(6)
	v_pk_add_f32 v[188:189], v[188:189], v[244:245]
	v_pk_add_f32 v[190:191], v[190:191], v[246:247]
	ds_read2_b32 v[244:245], v239 offset0:52 offset1:53
	ds_read2_b32 v[246:247], v239 offset0:54 offset1:55
	s_waitcnt lgkmcnt(6)
	v_pk_add_f32 v[176:177], v[176:177], v[248:249]
	v_pk_add_f32 v[178:179], v[178:179], v[250:251]
	ds_read2_b32 v[248:249], v239 offset0:36 offset1:37
	ds_read2_b32 v[250:251], v239 offset0:38 offset1:39
	s_waitcnt lgkmcnt(6)
	v_pk_add_f32 v[172:173], v[172:173], v[206:207]
	v_pk_add_f32 v[174:175], v[174:175], v[208:209]
	s_waitcnt lgkmcnt(4)
	v_pk_add_f32 v[168:169], v[168:169], v[240:241]
	v_pk_add_f32 v[170:171], v[170:171], v[242:243]
	s_waitcnt lgkmcnt(2)
	v_pk_add_f32 v[164:165], v[164:165], v[244:245]
	v_pk_add_f32 v[166:167], v[166:167], v[246:247]
	s_waitcnt lgkmcnt(0)
	v_pk_add_f32 v[160:161], v[160:161], v[248:249]
	v_pk_add_f32 v[162:163], v[162:163], v[250:251]
	s_branch .LBB0_318

; #define ATT_VLD(i_) lds_rd(stv, ((((i_) % (DV / 16)) * 2) + ((i_) / (DV / 16))) * 1024)
; template <int DV, int NMAP> ...
;     ...
;             bf16x8 v0 = ATT_VLD(0), v1 = ATT_VLD(1), v2 = ATT_VLD(2);
;             __builtin_amdgcn_sched_barrier(0);
;             if (t >= cw - 2) {
;                 const int tb = 64 * (t - cw + 2) + 8 * fq + 63 - qoff - fr;
; #pragma unroll
;                 for (int kb = 0; kb < 4; ++kb)
; #pragma unroll
;                     for (int qb = 0; qb < 2; ++qb)
; #pragma unroll
;                         for (int i = 0; i < 4; ++i) s[kb][qb][i] += tab[tb + 32 * (kb >> 1) + 4 * (kb & 1) + i - 16 * qb];
;             }
.LBB0_356:
	v_add_u32_e32 v149, 0x4000, v112
	ds_read_b128 v[136:139], v149 offset:0
	ds_read_b128 v[116:119], v149 offset:0x800
	ds_read_b128 v[112:115], v149 offset:0x1000
	s_cmp_lt_i32 s57, s37
	s_cbranch_scc1 .LBB0_349
	ds_read2_b32 v[174:175], v148 offset0:16 offset1:17
	ds_read2_b32 v[176:177], v148 offset0:18 offset1:19
	ds_read2_b32 v[178:179], v148 offset1:1
	ds_read2_b32 v[180:181], v148 offset0:2 offset1:3
	ds_read2_b32 v[182:183], v148 offset0:20 offset1:21
	ds_read2_b32 v[184:185], v148 offset0:22 offset1:23
	ds_read2_b32 v[186:187], v148 offset0:4 offset1:5
	ds_read2_b32 v[188:189], v148 offset0:6 offset1:7
	s_waitcnt lgkmcnt(6)
	v_pk_add_f32 v[132:133], v[132:133], v[174:175]
	v_pk_add_f32 v[134:135], v[134:135], v[176:177]
	ds_read2_b32 v[174:175], v148 offset0:48 offset1:49
	ds_read2_b32 v[176:177], v148 offset0:50 offset1:51
	s_waitcnt lgkmcnt(6)
	v_pk_add_f32 v[124:125], v[124:125], v[178:179]
	v_pk_add_f32 v[126:127], v[126:127], v[180:181]
	ds_read2_b32 v[178:179], v148 offset0:32 offset1:33
	ds_read2_b32 v[180:181], v148 offset0:34 offset1:35
	s_waitcnt lgkmcnt(6)
	v_pk_add_f32 v[128:129], v[128:129], v[182:183]
	v_pk_add_f32 v[130:131], v[130:131], v[184:185]
	ds_read2_b32 v[182:183], v148 offset0:52 offset1:53
	ds_read2_b32 v[184:185], v148 offset0:54 offset1:55
	s_waitcnt lgkmcnt(6)
	v_pk_add_f32 v[120:121], v[120:121], v[186:187]
	v_pk_add_f32 v[122:123], v[122:123], v[188:189]
	ds_read2_b32 v[186:187], v148 offset0:36 offset1:37
	ds_read2_b32 v[188:189], v148 offset0:38 offset1:39
	s_waitcnt lgkmcnt(6)
	v_pk_add_f32 v[108:109], v[108:109], v[174:175]
	v_pk_add_f32 v[110:111], v[110:111], v[176:177]
	s_waitcnt lgkmcnt(4)
	v_pk_add_f32 v[104:105], v[104:105], v[178:179]
	v_pk_add_f32 v[106:107], v[106:107], v[180:181]
	s_waitcnt lgkmcnt(2)
	v_pk_add_f32 v[100:101], v[100:101], v[182:183]
	v_pk_add_f32 v[102:103], v[102:103], v[184:185]
	s_waitcnt lgkmcnt(0)
	v_pk_add_f32 v[96:97], v[96:97], v[186:187]
	v_pk_add_f32 v[98:99], v[98:99], v[188:189]
	s_branch .LBB0_349
